# rg_in and gates: first K-iteration waits after a 16-store epilogue relaxed to the exact count (no store ack needed before the second load segment)
# speedup vs baseline: 1.0068x; 1.0035x over previous
.LBB0_110:
	ds_read_b128 v[156:159], v150
	ds_read_b128 v[160:163], v150 offset:1024
	ds_read_b128 v[164:167], v150 offset:2048
	ds_read_b128 v[168:171], v150 offset:3072
	ds_read_b128 v[172:175], v151
	ds_read_b128 v[184:187], v151 offset:1024
	ds_read_b128 v[188:191], v151 offset:2048
	ds_read_b128 v[192:195], v151 offset:3072
	s_add_u32 s8, s94, 0xfffc0080
	s_addc_u32 s9, s95, -1
	s_cmp_eq_u32 s42, 12
	s_cselect_b32 s39, s7, s9
	s_cselect_b32 s38, s16, s8
	s_cselect_b32 s37, s17, s29
	s_cselect_b32 s36, s18, s28
	v_lshl_add_u64 v[146:147], s[94:95], 0, v[138:139]
	s_add_i32 m0, s15, 0xc000
	ds_read_b128 v[196:199], v154
	ds_read_b128 v[200:203], v154 offset:1024
	ds_read_b128 v[204:207], v154 offset:2048
	ds_read_b128 v[208:211], v154 offset:3072
	ds_read_b128 v[212:215], v154 offset:4096
	ds_read_b128 v[216:219], v154 offset:5120
	ds_read_b128 v[220:223], v154 offset:6144
	ds_read_b128 v[224:227], v154 offset:7168
	global_load_lds_dwordx4 v[146:147], off
	v_lshl_add_u64 v[146:147], s[94:95], 0, v[140:141]
	s_add_i32 m0, s15, 0xe000
	s_nop 0
	global_load_lds_dwordx4 v[146:147], off
	s_cmp_eq_u32 s99, 0
	s_cbranch_scc1 .Ldpw_0_0a
	s_waitcnt vmcnt(24)
	s_branch .Ldpw_0_0b

.Ldpw_0_0b:
	s_waitcnt lgkmcnt(0)
	s_barrier
	s_setprio 1
	s_waitcnt lgkmcnt(0)
	v_mfma_f32_16x16x32_bf16 v[124:127], v[156:159], v[196:199], v[124:127]
	v_mfma_f32_16x16x32_bf16 v[120:123], v[164:167], v[196:199], v[120:123]
	v_mfma_f32_16x16x32_bf16 v[108:111], v[156:159], v[204:207], v[108:111]
	v_mfma_f32_16x16x32_bf16 v[104:107], v[164:167], v[204:207], v[104:107]
	v_mfma_f32_16x16x32_bf16 v[92:95], v[156:159], v[212:215], v[92:95]
	v_mfma_f32_16x16x32_bf16 v[88:91], v[164:167], v[212:215], v[88:91]
	v_mfma_f32_16x16x32_bf16 v[76:79], v[156:159], v[220:223], v[76:79]
	v_mfma_f32_16x16x32_bf16 v[72:75], v[164:167], v[220:223], v[72:75]
	v_mfma_f32_16x16x32_bf16 v[124:127], v[160:163], v[200:203], v[124:127]
	v_mfma_f32_16x16x32_bf16 v[120:123], v[168:171], v[200:203], v[120:123]
	v_mfma_f32_16x16x32_bf16 v[108:111], v[160:163], v[208:211], v[108:111]
	v_mfma_f32_16x16x32_bf16 v[104:107], v[168:171], v[208:211], v[104:107]
	v_mfma_f32_16x16x32_bf16 v[92:95], v[160:163], v[216:219], v[92:95]
	v_mfma_f32_16x16x32_bf16 v[88:91], v[168:171], v[216:219], v[88:91]
	v_mfma_f32_16x16x32_bf16 v[76:79], v[160:163], v[224:227], v[76:79]
	v_mfma_f32_16x16x32_bf16 v[72:75], v[168:171], v[224:227], v[72:75]
	s_setprio 0
	s_setprio 1
	v_mfma_f32_16x16x32_bf16 v[116:119], v[172:175], v[196:199], v[116:119]
	v_mfma_f32_16x16x32_bf16 v[112:115], v[188:191], v[196:199], v[112:115]
	v_mfma_f32_16x16x32_bf16 v[100:103], v[172:175], v[204:207], v[100:103]
	v_mfma_f32_16x16x32_bf16 v[96:99], v[188:191], v[204:207], v[96:99]
	v_mfma_f32_16x16x32_bf16 v[84:87], v[172:175], v[212:215], v[84:87]
	v_mfma_f32_16x16x32_bf16 v[80:83], v[188:191], v[212:215], v[80:83]
	v_mfma_f32_16x16x32_bf16 v[68:71], v[172:175], v[220:223], v[68:71]
	v_mfma_f32_16x16x32_bf16 v[64:67], v[188:191], v[220:223], v[64:67]
	v_mfma_f32_16x16x32_bf16 v[116:119], v[184:187], v[200:203], v[116:119]
	v_mfma_f32_16x16x32_bf16 v[112:115], v[192:195], v[200:203], v[112:115]
	v_mfma_f32_16x16x32_bf16 v[100:103], v[184:187], v[208:211], v[100:103]
	v_mfma_f32_16x16x32_bf16 v[96:99], v[192:195], v[208:211], v[96:99]
	v_mfma_f32_16x16x32_bf16 v[84:87], v[184:187], v[216:219], v[84:87]
	v_mfma_f32_16x16x32_bf16 v[80:83], v[192:195], v[216:219], v[80:83]
	v_mfma_f32_16x16x32_bf16 v[68:71], v[184:187], v[224:227], v[68:71]
	v_mfma_f32_16x16x32_bf16 v[64:67], v[192:195], v[224:227], v[64:67]
	s_setprio 0
	s_barrier
	s_add_i32 s8, s74, s45
	v_lshl_add_u64 v[146:147], s[36:37], 0, v[130:131]
	s_mov_b32 m0, s8
	ds_read_b128 v[196:199], v154 offset:16384
	ds_read_b128 v[200:203], v154 offset:17408
	ds_read_b128 v[204:207], v154 offset:18432
	ds_read_b128 v[208:211], v154 offset:19456
	ds_read_b128 v[212:215], v154 offset:20480
	ds_read_b128 v[216:219], v154 offset:21504
	ds_read_b128 v[220:223], v154 offset:22528
	ds_read_b128 v[224:227], v154 offset:23552
	global_load_lds_dwordx4 v[146:147], off
	s_add_i32 m0, s8, 0x2000
	s_add_u32 s8, s36, 0x40000
	v_lshl_add_u64 v[228:229], s[36:37], 0, v[134:135]
	s_addc_u32 s9, s37, 0
	s_add_i32 s43, s75, s45
	global_load_lds_dwordx4 v[228:229], off
	v_lshl_add_u64 v[230:231], s[8:9], 0, v[130:131]
	s_mov_b32 m0, s43
	v_lshl_add_u64 v[232:233], s[38:39], 0, v[132:133]
	global_load_lds_dwordx4 v[230:231], off
	v_lshl_add_u64 v[230:231], s[8:9], 0, v[134:135]
	s_add_i32 m0, s43, 0x2000
	s_nop 0
	global_load_lds_dwordx4 v[230:231], off
	v_lshl_add_u64 v[230:231], s[38:39], 0, v[128:129]
	s_mov_b32 m0, s15
	s_nop 0
	global_load_lds_dwordx4 v[230:231], off
	s_mov_b32 m0, s48
	s_nop 0
	global_load_lds_dwordx4 v[232:233], off
	s_cmp_eq_u32 s99, 0
	s_cbranch_scc1 .Ldpw_0_1a
	s_waitcnt vmcnt(24)
	s_branch .Ldpw_0_1b

.LBB0_458:
	s_add_u32 s19, s82, s18
	s_addc_u32 s29, s83, 0
	s_add_u32 s38, s19, 0x100
	s_addc_u32 s39, s29, 0
	s_and_b64 s[8:9], s[36:37], exec
	s_cselect_b32 s49, s1, s39
	s_cselect_b32 s48, s16, s38
	s_add_u32 s8, s80, s18
	s_addc_u32 s9, s81, 0
	s_add_u32 s18, s8, 0x100
	s_addc_u32 s38, s9, 0
	s_and_b64 s[8:9], s[36:37], exec
	s_cselect_b32 s51, s17, s38
	s_cselect_b32 s50, s28, s18
	s_add_u32 s70, s19, 0x40080
	s_addc_u32 s71, s29, 0
	s_add_i32 vcc_hi, s91, s33
	ds_read_b128 v[28:31], v173
	ds_read_b128 v[32:35], v173 offset:1024
	ds_read_b128 v[40:43], v173 offset:2048
	ds_read_b128 v[44:47], v173 offset:3072
	ds_read_b128 v[144:147], v174
	ds_read_b128 v[148:151], v174 offset:1024
	ds_read_b128 v[166:169], v174 offset:2048
	ds_read_b128 v[188:191], v174 offset:3072
	s_add_i32 m0, s41, 0xc000
	s_add_i32 s76, s41, 0xe000
	s_add_i32 s97, vcc_hi, 0x2000
	s_add_u32 s68, s50, 0x10000
	s_addc_u32 s69, s51, 0
	s_add_i32 s9, s92, s33
	s_add_i32 s8, s9, 0x2000
	s_add_i32 vcc_lo, 0, 0x18000
	s_add_i32 s57, 0, 0x1c000
	s_add_u32 s38, s48, 0x40000
	s_addc_u32 s39, s49, 0
	s_add_i32 s47, vcc_lo, s33
	s_add_i32 s19, s47, 0x2000
	s_add_u32 s36, s50, 0x10080
	s_addc_u32 s37, s51, 0
	s_add_i32 s29, s57, s33
	s_add_i32 s18, s29, 0x2000
	v_lshl_add_u64 v[224:225], s[70:71], 0, v[160:161]
	ds_read_b128 v[192:195], v175
	ds_read_b128 v[196:199], v175 offset:1024
	ds_read_b128 v[200:203], v175 offset:2048
	ds_read_b128 v[204:207], v175 offset:3072
	ds_read_b128 v[208:211], v175 offset:4096
	ds_read_b128 v[212:215], v175 offset:5120
	ds_read_b128 v[216:219], v175 offset:6144
	ds_read_b128 v[220:223], v175 offset:7168
	global_load_lds_dwordx4 v[224:225], off
	v_lshl_add_u64 v[224:225], s[70:71], 0, v[156:157]
	s_mov_b32 m0, s76
	s_nop 0
	global_load_lds_dwordx4 v[224:225], off
	s_cmp_eq_u32 s99, 0
	s_cbranch_scc1 .Ldpw_1_0a
	s_waitcnt vmcnt(24)
	s_branch .Ldpw_1_0b

.Ldpw_1_0b:
	s_waitcnt lgkmcnt(0)
	s_barrier
	s_setprio 1
	s_waitcnt lgkmcnt(0)
	v_mfma_f32_16x16x32_bf16 v[140:143], v[28:31], v[192:195], v[140:143]
	v_mfma_f32_16x16x32_bf16 v[132:135], v[40:43], v[192:195], v[132:135]
	v_mfma_f32_16x16x32_bf16 v[124:127], v[28:31], v[200:203], v[124:127]
	v_mfma_f32_16x16x32_bf16 v[116:119], v[40:43], v[200:203], v[116:119]
	v_mfma_f32_16x16x32_bf16 v[108:111], v[28:31], v[208:211], v[108:111]
	v_mfma_f32_16x16x32_bf16 v[100:103], v[40:43], v[208:211], v[100:103]
	v_mfma_f32_16x16x32_bf16 v[92:95], v[28:31], v[216:219], v[92:95]
	v_mfma_f32_16x16x32_bf16 v[84:87], v[40:43], v[216:219], v[84:87]
	v_mfma_f32_16x16x32_bf16 v[140:143], v[32:35], v[196:199], v[140:143]
	v_mfma_f32_16x16x32_bf16 v[132:135], v[44:47], v[196:199], v[132:135]
	v_mfma_f32_16x16x32_bf16 v[124:127], v[32:35], v[204:207], v[124:127]
	v_mfma_f32_16x16x32_bf16 v[116:119], v[44:47], v[204:207], v[116:119]
	v_mfma_f32_16x16x32_bf16 v[108:111], v[32:35], v[212:215], v[108:111]
	v_mfma_f32_16x16x32_bf16 v[100:103], v[44:47], v[212:215], v[100:103]
	v_mfma_f32_16x16x32_bf16 v[92:95], v[32:35], v[220:223], v[92:95]
	v_mfma_f32_16x16x32_bf16 v[84:87], v[44:47], v[220:223], v[84:87]
	s_setprio 0
	s_setprio 1
	v_mfma_f32_16x16x32_bf16 v[136:139], v[144:147], v[192:195], v[136:139]
	v_mfma_f32_16x16x32_bf16 v[128:131], v[166:169], v[192:195], v[128:131]
	v_mfma_f32_16x16x32_bf16 v[120:123], v[144:147], v[200:203], v[120:123]
	v_mfma_f32_16x16x32_bf16 v[112:115], v[166:169], v[200:203], v[112:115]
	v_mfma_f32_16x16x32_bf16 v[104:107], v[144:147], v[208:211], v[104:107]
	v_mfma_f32_16x16x32_bf16 v[96:99], v[166:169], v[208:211], v[96:99]
	v_mfma_f32_16x16x32_bf16 v[88:91], v[144:147], v[216:219], v[88:91]
	v_mfma_f32_16x16x32_bf16 v[80:83], v[166:169], v[216:219], v[80:83]
	v_mfma_f32_16x16x32_bf16 v[136:139], v[148:151], v[196:199], v[136:139]
	v_mfma_f32_16x16x32_bf16 v[128:131], v[188:191], v[196:199], v[128:131]
	v_mfma_f32_16x16x32_bf16 v[120:123], v[148:151], v[204:207], v[120:123]
	v_mfma_f32_16x16x32_bf16 v[112:115], v[188:191], v[204:207], v[112:115]
	v_mfma_f32_16x16x32_bf16 v[104:107], v[148:151], v[212:215], v[104:107]
	v_mfma_f32_16x16x32_bf16 v[96:99], v[188:191], v[212:215], v[96:99]
	v_mfma_f32_16x16x32_bf16 v[88:91], v[148:151], v[220:223], v[88:91]
	v_mfma_f32_16x16x32_bf16 v[80:83], v[188:191], v[220:223], v[80:83]
	s_setprio 0
	s_barrier
	s_mov_b32 m0, vcc_hi
	v_lshl_add_u64 v[224:225], s[50:51], 0, v[158:159]
	ds_read_b128 v[192:195], v175 offset:16384
	ds_read_b128 v[196:199], v175 offset:17408
	ds_read_b128 v[200:203], v175 offset:18432
	ds_read_b128 v[204:207], v175 offset:19456
	ds_read_b128 v[208:211], v175 offset:20480
	ds_read_b128 v[212:215], v175 offset:21504
	ds_read_b128 v[216:219], v175 offset:22528
	ds_read_b128 v[220:223], v175 offset:23552
	global_load_lds_dwordx4 v[224:225], off
	v_lshl_add_u64 v[226:227], s[50:51], 0, v[154:155]
	s_mov_b32 m0, s97
	v_lshl_add_u64 v[228:229], s[68:69], 0, v[158:159]
	global_load_lds_dwordx4 v[226:227], off
	s_mov_b32 m0, s9
	v_lshl_add_u64 v[230:231], s[48:49], 0, v[156:157]
	global_load_lds_dwordx4 v[228:229], off
	v_lshl_add_u64 v[228:229], s[68:69], 0, v[154:155]
	s_mov_b32 m0, s8
	s_nop 0
	global_load_lds_dwordx4 v[228:229], off
	v_lshl_add_u64 v[228:229], s[48:49], 0, v[160:161]
	s_mov_b32 m0, s41
	s_nop 0
	global_load_lds_dwordx4 v[228:229], off
	s_mov_b32 m0, s77
	s_nop 0
	global_load_lds_dwordx4 v[230:231], off
	s_cmp_eq_u32 s99, 0
	s_cbranch_scc1 .Ldpw_1_1a
	s_waitcnt vmcnt(24)
	s_branch .Ldpw_1_1b
